# v47 + P2a gla chunk MFMA stage: 8 KdT fragment reads issued up front, 4 independent accumulators, counted lgkmcnt waits, stores at the end
# baseline (speedup 1.0000x reference)
; #define LBAR() do { asm volatile("s_waitcnt lgkmcnt(0)" ::: "memory"); __builtin_amdgcn_s_barrier(); asm volatile("" ::: "memory"); } while (0)
; __device__ __forceinline__ f32x4 mma16(bf16x8 a, bf16x8 b, f32x4 c) { return __builtin_amdgcn_mfma_f32_16x16x32_bf16(a, b, c, 0, 0, 0); }
; template <int MODE>
; __device__ __forceinline__ void gla_chunk_item(int item, const u16* PROJ, u16* MIXIN, const float* wgate, const float* bgate, const float* ggla, float* GS, float* GDEC, const u16* GSB, LAS unsigned char* lds, GateW& gw_) {
;     ...
;         LBAR();
;         const bf16x8 av0 = gfrag(RV, RP, 0, 16 * w + (lane & 15), lane), av1 = gfrag(RV, RP, 32, 16 * w + (lane & 15), lane);
; #pragma unroll
;         for (int dt = 0; dt < 4; ++dt) { f32x4 s = (f32x4){0.f, 0.f, 0.f, 0.f};
;             s = mma16(av0, frag(KdT, dt * 16, LD, 0, lane), s); s = mma16(av1, frag(KdT, dt * 16, LD, 32, lane), s);
;             *(f32x4*)(gs + (size_t)(16 * dt + (lane & 15)) * 128 + 16 * w + (lane >> 4) * 4) = s; }
;         LBAR();
.LBB0_246:
	v_lshlrev_b32_e32 v0, 1, v64
	v_lshl_or_b32 v0, s54, 5, v0
	s_waitcnt lgkmcnt(0)
	s_barrier
	v_add_u32_e32 v0, v114, v0
	ds_read_u16 v4, v0 offset:53248
	ds_read_u16 v5, v0 offset:53512
	ds_read_u16 v1, v0 offset:53776
	ds_read_u16 v6, v0 offset:54040
	ds_read_u16 v2, v0 offset:54304
	ds_read_u16 v7, v0 offset:54568
	ds_read_u16 v3, v0 offset:54832
	ds_read_u16 v8, v0 offset:55096
	ds_read_u16 v9, v0 offset:61696
	ds_read_u16 v10, v0 offset:61960
	ds_read_u16 v11, v0 offset:62224
	ds_read_u16 v12, v0 offset:62488
	ds_read_u16 v13, v0 offset:62752
	ds_read_u16 v14, v0 offset:63016
	ds_read_u16 v15, v0 offset:63280
	ds_read_u16 v16, v0 offset:63544
	s_waitcnt lgkmcnt(8)
	v_perm_b32 v3, v8, v3, s31
	v_perm_b32 v2, v7, v2, s31
	v_perm_b32 v1, v6, v1, s31
	v_perm_b32 v0, v5, v4, s31
	ds_read_b128 v[204:207], v115 offset:18432
	ds_read_b128 v[208:211], v115 offset:18496
	ds_read_b128 v[212:215], v116 offset:18432
	ds_read_b128 v[216:219], v116 offset:18496
	s_waitcnt lgkmcnt(8)
	v_perm_b32 v5, v12, v11, s31
	v_perm_b32 v4, v10, v9, s31
	ds_read_b128 v[220:223], v117 offset:18432
	ds_read_b128 v[224:227], v117 offset:18496
	ds_read_b128 v[228:231], v118 offset:18432
	ds_read_b128 v[232:235], v118 offset:18496
	s_waitcnt lgkmcnt(8)
	v_perm_b32 v7, v16, v15, s31
	v_perm_b32 v6, v14, v13, s31
	s_lshl_b64 s[56:57], s[6:7], 15
	s_add_u32 s6, s28, s56
	s_addc_u32 s55, s29, s57
	s_lshl_b32 s54, s54, 6
	s_add_u32 s54, s6, s54
	s_addc_u32 s55, s55, 0
	v_lshlrev_b32_e32 v52, 2, v66
	v_lshl_add_u64 v[16:17], s[54:55], 0, v[52:53]
	v_mov_b32_e32 v81, v53
	v_mov_b32_e32 v83, v53
	v_mov_b32_e32 v85, v53
	v_mov_b32_e32 v87, v53
	s_mov_b64 s[88:89], s[64:65]
	s_waitcnt lgkmcnt(6)
	v_mfma_f32_16x16x32_bf16 v[240:243], v[0:3], v[204:207], 0
	s_waitcnt lgkmcnt(4)
	v_mfma_f32_16x16x32_bf16 v[244:247], v[0:3], v[212:215], 0
	s_waitcnt lgkmcnt(2)
	v_mfma_f32_16x16x32_bf16 v[248:251], v[0:3], v[220:223], 0
	s_waitcnt lgkmcnt(0)
	v_mfma_f32_16x16x32_bf16 v[252:255], v[0:3], v[228:231], 0
	v_mfma_f32_16x16x32_bf16 v[240:243], v[4:7], v[208:211], v[240:243]
	v_mfma_f32_16x16x32_bf16 v[244:247], v[4:7], v[216:219], v[244:247]
	v_mfma_f32_16x16x32_bf16 v[248:251], v[4:7], v[224:227], v[248:251]
	v_mfma_f32_16x16x32_bf16 v[252:255], v[4:7], v[232:235], v[252:255]
	v_lshl_add_u64 v[8:9], v[16:17], 0, v[80:81]
	v_lshl_add_u64 v[10:11], v[16:17], 0, v[82:83]
	v_lshl_add_u64 v[12:13], v[16:17], 0, v[84:85]
	v_lshl_add_u64 v[14:15], v[16:17], 0, v[86:87]
	s_nop 7
	s_nop 3
	global_store_dwordx4 v[8:9], v[240:243], off
	global_store_dwordx4 v[10:11], v[244:247], off
	global_store_dwordx4 v[12:13], v[248:251], off
	s_nop 3
	global_store_dwordx4 v[14:15], v[252:255], off
	s_waitcnt lgkmcnt(0)
	s_barrier
	s_cbranch_execnz .LBB0_223
	s_branch .LBB0_236
